# v99: v93 with FoX gate rows prefetched by LDS-DMA during the last two key tiles and read from LDS in the epilogue (no exposed global gate loads)
# speedup vs baseline: 1.0096x; 1.0096x over previous
; #define ATT_WAITV(n) asm volatile("s_waitcnt vmcnt(" #n ")" ::: "memory")
; template <int MODE>
; __device__ __forceinline__ void attn_unit(const Params& P, LAS unsigned char* lds, const int b, const int h, const int qb) {
;     ...
;     for (int kt = kt0; kt < nt; ++kt) {
;         const int rel = kt - kt0, cur = rel & (AL_NBUF - 1);
;         if (kt + 2 < nt) { if (FOX) ATT_WAITV(10); else ATT_WAITV(8); } else if (kt + 1 < nt) { if (FOX) ATT_WAITV(5); else ATT_WAITV(4); } else ATT_WAITV(0);
;         __builtin_amdgcn_s_barrier(); asm volatile("" ::: "memory");
;         if (kt + AL_PD < nt) ATT_DMA(kt + AL_PD, (rel + AL_PD) & (AL_NBUF - 1));
.LBB0_455:
	s_add_i32 s8, s40, 3
	s_sub_i32 s8, s8, s1
	s_cmp_gt_u32 s8, 1
	s_cbranch_scc1 .Lfox_znone
	s_add_i32 s41, s67, -1
	s_and_b32 s41, s41, 3
	s_lshl_b32 s41, s41, 15
	s_sub_i32 s70, s58, 0x100
	s_lshl_b32 s70, s70, 2
	s_add_i32 s70, s70, s41
	s_addk_i32 s70, 0x100
	v_and_b32_e32 v236, 0xfffff07f, v182
	s_nop 0
	v_readfirstlane_b32 s41, v236
	s_lshl_b32 s9, s8, 12
	s_lshl_b32 s41, s41, 1
	s_add_i32 s41, s41, s9
	s_add_u32 s68, s84, s64
	s_addc_u32 s69, s85, s65
	s_add_u32 s68, s68, s41
	s_addc_u32 s69, s69, 0
	v_and_b32_e32 v236, 63, v178
	v_lshrrev_b32_e32 v237, 4, v236
	v_and_b32_e32 v236, 15, v236
	v_xor_b32_e32 v236, v237, v236
	v_lshlrev_b32_e32 v236, 4, v236
	v_lshl_add_u32 v236, v237, 8, v236
	s_mov_b32 m0, s70
	v_xor_b32_e32 v237, 0x40, v236
	v_xor_b32_e32 v238, 0x80, v236
	v_xor_b32_e32 v239, 0xc0, v236
	global_load_lds_dwordx4 v236, s[68:69]
	global_load_lds_dwordx4 v237, s[68:69] offset:1024
	global_load_lds_dwordx4 v238, s[68:69] offset:2048
	global_load_lds_dwordx4 v239, s[68:69] offset:3072

; __device__ __forceinline__ float silu_f(float z) { return z * __builtin_amdgcn_rcpf(1.0f + __builtin_amdgcn_exp2f(-LOG2E * z)); }
; __device__ __forceinline__ float bf_lo(unsigned v) { return __uint_as_float(v << 16); }
; __device__ __forceinline__ float bf_hi(unsigned v) { return __uint_as_float(v & 0xffff0000u); }
; template <int MODE>
; __device__ __forceinline__ void attn_unit(const Params& P, LAS unsigned char* lds, const int b, const int h, const int qb) {
;     ...
;     bf16_t* mix = (bf16_t*)(P.ws + WS_MIX) + (tokbase + q) * DM + colO;
;     const bf16_t* zp = Zb + (size_t)q * RS;
;     const float inv1 = 1.0f / (l1 + __shfl_xor(l1, 32));
;     u32x2 zv[4][4]; f32x4 gv[4][4];
;     if (FOX || mp == 0) {
; #pragma unroll
;         for (int d = 0; d < 4; ++d)
; #pragma unroll
;             for (int a = 0; a < 4; ++a) { const int d0 = 32 * d + 8 * a + 4 * hh; zv[d][a] = *(const u32x2*)(zp + d0); if (!FOX) gv[d][a] = *(const f32x4*)(P.in[I_DON] + d0); }
;     }
;     asm volatile("" ::: "memory");
;     if (FOX) {
; #pragma unroll
;         for (int d = 0; d < 4; ++d)
; #pragma unroll
;             for (int a = 0; a < 4; ++a) { const int d0 = 32 * d + 8 * a + 4 * hh; const u32x2 z2 = zv[d][a];
;                 const float o0 = O[d][4 * a] * inv1 * silu_f(bf_lo(z2.x)), o1 = O[d][4 * a + 1] * inv1 * silu_f(bf_hi(z2.x));
;                 const float o2 = O[d][4 * a + 2] * inv1 * silu_f(bf_lo(z2.y)), o3 = O[d][4 * a + 3] * inv1 * silu_f(bf_hi(z2.y));
;                 u32x2 ov; ov.x = cvt_pk_bf16(o0, o1); ov.y = cvt_pk_bf16(o2, o3); *(u32x2*)(mix + d0) = ov; }
.LBB0_465:
	s_lshr_b32 s0, s12, 3
	s_add_u32 s8, s84, s64
	s_addc_u32 s9, s85, s65
	v_lshl_add_u64 v[2:3], v[182:183], 1, s[8:9]
	v_mov_b32_e32 v97, v1
	v_lshl_add_u64 v[2:3], v[2:3], 0, v[96:97]
	v_and_b32_e32 v236, 31, v178
	v_lshrrev_b32_e32 v237, 4, v236
	v_add_u32_e32 v237, s39, v237
	v_and_b32_e32 v237, 3, v237
	v_lshlrev_b32_e32 v237, 15, v237
	v_and_b32_e32 v236, 15, v236
	v_lshl_add_u32 v237, v236, 8, v237
	v_lshl_add_u32 v237, v236, 4, v237
	v_lshrrev_b32_e32 v236, 6, v178
	v_lshl_add_u32 v237, v236, 12, v237
	v_and_b32_e32 v236, 32, v178
	v_lshrrev_b32_e32 v236, 2, v236
	v_add3_u32 v237, v237, v236, v232
	ds_read_b64 v[94:95], v237
	v_xor_b32_e32 v239, 0x10, v237
	ds_read_b64 v[98:99], v239
	v_and_b32_e32 v6, 64, v179
	v_xor_b32_e32 v0, 32, v179
	v_add_u32_e32 v6, 64, v6
	v_cmp_lt_i32_e32 vcc, v0, v6
	v_xor_b32_e32 v238, 0x20, v237
	ds_read_b64 v[100:101], v238
	v_xor_b32_e32 v239, 0x30, v237
	ds_read_b64 v[92:93], v239
	v_xor_b32_e32 v238, 0x40, v237
	ds_read_b64 v[90:91], v238
	v_xor_b32_e32 v239, 0x50, v237
	ds_read_b64 v[88:89], v239
	v_xor_b32_e32 v238, 0x60, v237
	ds_read_b64 v[86:87], v238
	v_xor_b32_e32 v239, 0x70, v237
	ds_read_b64 v[84:85], v239
	v_xor_b32_e32 v238, 0x80, v237
	ds_read_b64 v[82:83], v238
	v_xor_b32_e32 v239, 0x90, v237
	ds_read_b64 v[80:81], v239
	v_xor_b32_e32 v238, 0xa0, v237
	ds_read_b64 v[14:15], v238
	v_xor_b32_e32 v239, 0xb0, v237
	ds_read_b64 v[12:13], v239
	v_xor_b32_e32 v238, 0xc0, v237
	ds_read_b64 v[10:11], v238
	v_xor_b32_e32 v239, 0xd0, v237
	ds_read_b64 v[8:9], v239
	v_xor_b32_e32 v238, 0xe0, v237
	ds_read_b64 v[6:7], v238
	s_nop 0
	v_xor_b32_e32 v239, 0xf0, v237
	ds_read_b64 v[2:3], v239
	v_cndmask_b32_e32 v0, v179, v0, vcc
	v_lshlrev_b32_e32 v0, 2, v0
	ds_bpermute_b32 v0, v0, v191
	s_mov_b32 s1, s13
	s_lshl_b64 s[0:1], s[0:1], 25
	s_add_u32 s0, s20, s0
	v_lshlrev_b64 v[4:5], 12, v[180:181]
	s_addc_u32 s1, s21, s1
	s_waitcnt lgkmcnt(0)
	v_add_f32_e32 v0, v191, v0
	v_lshl_add_u64 v[4:5], s[0:1], 0, v[4:5]
	v_div_scale_f32 v102, s[0:1], v0, v0, 1.0
	v_rcp_f32_e32 v103, v102
	s_lshl_b32 s8, s12, 8
	s_and_b32 s12, s8, 0x700
	v_lshl_add_u64 v[4:5], v[4:5], 0, s[12:13]
	v_lshl_add_u64 v[4:5], v[4:5], 0, v[96:97]
	v_lshl_add_u64 v[226:227], v[4:5], 0, v[96:97]
	v_fma_f32 v97, -v102, v103, 1.0
	v_div_scale_f32 v96, vcc, 1.0, v0, 1.0
	v_fmac_f32_e32 v103, v97, v103
	v_mul_f32_e32 v97, v96, v103
	v_fma_f32 v104, -v102, v97, v96
	v_fmac_f32_e32 v97, v104, v103
	v_fma_f32 v96, -v102, v97, v96
	v_div_fmas_f32 v96, v96, v103, v97
	v_div_fixup_f32 v0, v96, v0, 1.0
	v_pk_mul_f32 v[64:65], v[64:65], v[0:1] op_sel_hi:[1,0]
	v_pk_mul_f32 v[66:67], v[66:67], v[0:1] op_sel_hi:[1,0]
	v_pk_mul_f32 v[68:69], v[68:69], v[0:1] op_sel_hi:[1,0]
	v_pk_mul_f32 v[48:49], v[48:49], v[0:1] op_sel_hi:[1,0]
	v_pk_mul_f32 v[50:51], v[50:51], v[0:1] op_sel_hi:[1,0]
	v_pk_mul_f32 v[52:53], v[52:53], v[0:1] op_sel_hi:[1,0]
	v_pk_mul_f32 v[32:33], v[32:33], v[0:1] op_sel_hi:[1,0]
	v_pk_mul_f32 v[34:35], v[34:35], v[0:1] op_sel_hi:[1,0]
	v_pk_mul_f32 v[36:37], v[36:37], v[0:1] op_sel_hi:[1,0]
	s_mov_b64 s[8:9], 0
	s_waitcnt vmcnt(0)
	s_waitcnt lgkmcnt(0)
	v_lshlrev_b32_e32 v96, 16, v94
	v_and_b32_e32 v97, 0xffff0000, v94
	v_lshlrev_b32_e32 v94, 16, v95
	v_and_b32_e32 v95, 0xffff0000, v95
	v_mul_f32_e32 v104, 0xbfb8aa3b, v96
	v_mul_f32_e32 v105, 0xbfb8aa3b, v97
	v_mul_f32_e32 v106, 0xbfb8aa3b, v94
	v_mul_f32_e32 v107, 0xbfb8aa3b, v95
	v_exp_f32_e32 v104, v104
	v_exp_f32_e32 v105, v105
	v_exp_f32_e32 v106, v106
	v_exp_f32_e32 v107, v107
	v_add_f32_e32 v104, 1.0, v104
	v_add_f32_e32 v105, 1.0, v105
	v_add_f32_e32 v106, 1.0, v106
	v_add_f32_e32 v107, 1.0, v107
	v_lshlrev_b32_e32 v102, 16, v98
	v_and_b32_e32 v103, 0xffff0000, v98
	v_rcp_f32_e32 v104, v104
	v_rcp_f32_e32 v105, v105
	v_rcp_f32_e32 v106, v106
	v_rcp_f32_e32 v107, v107
	v_lshlrev_b32_e32 v98, 16, v99
	v_and_b32_e32 v99, 0xffff0000, v99
	v_mul_f32_e32 v108, 0xbfb8aa3b, v102
	v_mul_f32_e32 v109, 0xbfb8aa3b, v103
	v_mul_f32_e32 v110, 0xbfb8aa3b, v98
	v_mul_f32_e32 v111, 0xbfb8aa3b, v99
	v_exp_f32_e32 v108, v108
	v_exp_f32_e32 v109, v109
	v_exp_f32_e32 v110, v110
	v_exp_f32_e32 v111, v111
	v_pk_mul_f32 v[96:97], v[104:105], v[96:97]
	v_pk_mul_f32 v[94:95], v[106:107], v[94:95]
	v_pk_mul_f32 v[64:65], v[64:65], v[96:97]
	v_pk_mul_f32 v[66:67], v[66:67], v[94:95]
	v_add_f32_e32 v108, 1.0, v108
	v_add_f32_e32 v109, 1.0, v109
	v_cvt_pk_bf16_f32 v64, v64, v65
	v_cvt_pk_bf16_f32 v65, v66, v67
	v_rcp_f32_e32 v108, v108
	v_mov_b32_e32 v236, v64
	v_mov_b32_e32 v237, v65
	v_rcp_f32_e32 v109, v109
	v_add_f32_e32 v64, 1.0, v110
	v_add_f32_e32 v65, 1.0, v111
	v_rcp_f32_e32 v64, v64
	v_rcp_f32_e32 v65, v65
	v_pk_mul_f32 v[66:67], v[108:109], v[102:103]
	v_pk_mul_f32 v[64:65], v[64:65], v[98:99]
	v_pk_mul_f32 v[66:67], v[68:69], v[66:67]
	v_pk_mul_f32 v[68:69], v[70:71], v[0:1] op_sel_hi:[1,0]
	v_cvt_pk_bf16_f32 v66, v66, v67
	v_pk_mul_f32 v[64:65], v[68:69], v[64:65]
	v_lshlrev_b32_e32 v70, 16, v101
	v_cvt_pk_bf16_f32 v67, v64, v65
	v_lshlrev_b32_e32 v64, 16, v100
	v_mul_f32_e32 v65, 0xbfb8aa3b, v64
	v_mov_b32_e32 v238, v66
	v_mov_b32_e32 v239, v67
	s_nop 1
	v_permlane32_swap_b32 v236, v238
	v_permlane32_swap_b32 v237, v239
	global_store_dwordx4 v[226:227], v[236:239], off
	v_exp_f32_e32 v66, v65
	v_and_b32_e32 v65, 0xffff0000, v100
	v_mul_f32_e32 v67, 0xbfb8aa3b, v65
	v_and_b32_e32 v71, 0xffff0000, v101
	v_exp_f32_e32 v67, v67
	v_pk_mul_f32 v[68:69], v[72:73], v[0:1] op_sel_hi:[1,0]
	v_mul_f32_e32 v72, 0xbfb8aa3b, v70
	v_mul_f32_e32 v73, 0xbfb8aa3b, v71
	v_exp_f32_e32 v72, v72
	v_exp_f32_e32 v73, v73
	v_add_f32_e32 v66, 1.0, v66
	v_add_f32_e32 v67, 1.0, v67
	v_rcp_f32_e32 v66, v66
; __device__ __forceinline__ float silu_f(float z) { return z * __builtin_amdgcn_rcpf(1.0f + __builtin_amdgcn_exp2f(-LOG2E * z)); }
; __device__ __forceinline__ float bf_lo(unsigned v) { return __uint_as_float(v << 16); }
; __device__ __forceinline__ float bf_hi(unsigned v) { return __uint_as_float(v & 0xffff0000u); }
; template <int MODE>
; __device__ __forceinline__ void attn_unit(const Params& P, LAS unsigned char* lds, const int b, const int h, const int qb) {
;     ...
;     if (FOX) {
; #pragma unroll
;         for (int d = 0; d < 4; ++d)
; #pragma unroll
;             for (int a = 0; a < 4; ++a) { const int d0 = 32 * d + 8 * a + 4 * hh; const u32x2 z2 = zv[d][a];
;                 const float o0 = O[d][4 * a] * inv1 * silu_f(bf_lo(z2.x)), o1 = O[d][4 * a + 1] * inv1 * silu_f(bf_hi(z2.x));
;                 const float o2 = O[d][4 * a + 2] * inv1 * silu_f(bf_lo(z2.y)), o3 = O[d][4 * a + 3] * inv1 * silu_f(bf_hi(z2.y));
;                 u32x2 ov; ov.x = cvt_pk_bf16(o0, o1); ov.y = cvt_pk_bf16(o2, o3); *(u32x2*)(mix + d0) = ov; }
	v_rcp_f32_e32 v67, v67
	v_add_f32_e32 v72, 1.0, v72
	v_add_f32_e32 v73, 1.0, v73
	v_rcp_f32_e32 v72, v72
	v_rcp_f32_e32 v73, v73
	v_pk_mul_f32 v[64:65], v[66:67], v[64:65]
	v_pk_mul_f32 v[66:67], v[74:75], v[0:1] op_sel_hi:[1,0]
	v_pk_mul_f32 v[64:65], v[68:69], v[64:65]
	v_pk_mul_f32 v[68:69], v[72:73], v[70:71]
	v_cvt_pk_bf16_f32 v64, v64, v65
	v_pk_mul_f32 v[66:67], v[66:67], v[68:69]
	v_lshlrev_b32_e32 v70, 16, v93
	v_cvt_pk_bf16_f32 v65, v66, v67
	v_mov_b32_e32 v240, v64
	v_mov_b32_e32 v241, v65
	v_lshlrev_b32_e32 v64, 16, v92
	v_mul_f32_e32 v65, 0xbfb8aa3b, v64
	v_exp_f32_e32 v66, v65
	v_and_b32_e32 v65, 0xffff0000, v92
	v_mul_f32_e32 v67, 0xbfb8aa3b, v65
	v_and_b32_e32 v71, 0xffff0000, v93
	v_exp_f32_e32 v67, v67
	v_mul_f32_e32 v72, 0xbfb8aa3b, v70
	v_mul_f32_e32 v73, 0xbfb8aa3b, v71
	v_exp_f32_e32 v72, v72
	v_exp_f32_e32 v73, v73
	v_add_f32_e32 v66, 1.0, v66
	v_add_f32_e32 v67, 1.0, v67
	v_rcp_f32_e32 v66, v66
	v_rcp_f32_e32 v67, v67
	v_add_f32_e32 v72, 1.0, v72
	v_add_f32_e32 v73, 1.0, v73
	v_rcp_f32_e32 v72, v72
	v_rcp_f32_e32 v73, v73
	v_pk_mul_f32 v[68:69], v[76:77], v[0:1] op_sel_hi:[1,0]
	v_pk_mul_f32 v[64:65], v[66:67], v[64:65]
	v_pk_mul_f32 v[66:67], v[78:79], v[0:1] op_sel_hi:[1,0]
	v_pk_mul_f32 v[64:65], v[68:69], v[64:65]
	v_pk_mul_f32 v[68:69], v[72:73], v[70:71]
	v_cvt_pk_bf16_f32 v64, v64, v65
	v_pk_mul_f32 v[66:67], v[66:67], v[68:69]
	v_lshlrev_b32_e32 v68, 16, v91
	v_cvt_pk_bf16_f32 v65, v66, v67
	v_mov_b32_e32 v242, v64
	v_mov_b32_e32 v243, v65
	s_nop 1
	v_permlane32_swap_b32 v240, v242
	v_permlane32_swap_b32 v241, v243
	global_store_dwordx4 v[226:227], v[240:243], off offset:32
	v_lshlrev_b32_e32 v64, 16, v90
	v_mul_f32_e32 v65, 0xbfb8aa3b, v64
	v_exp_f32_e32 v66, v65
	v_and_b32_e32 v65, 0xffff0000, v90
	v_mul_f32_e32 v67, 0xbfb8aa3b, v65
	v_and_b32_e32 v69, 0xffff0000, v91
	v_exp_f32_e32 v67, v67
	v_mul_f32_e32 v70, 0xbfb8aa3b, v68
	v_mul_f32_e32 v71, 0xbfb8aa3b, v69
	v_exp_f32_e32 v70, v70
	v_exp_f32_e32 v71, v71
	v_add_f32_e32 v66, 1.0, v66
	v_add_f32_e32 v67, 1.0, v67
	v_rcp_f32_e32 v66, v66
	v_rcp_f32_e32 v67, v67
	v_add_f32_e32 v70, 1.0, v70
	v_add_f32_e32 v71, 1.0, v71
	v_rcp_f32_e32 v70, v70
	v_rcp_f32_e32 v71, v71
	v_pk_mul_f32 v[64:65], v[66:67], v[64:65]
	s_nop 0
	v_pk_mul_f32 v[48:49], v[48:49], v[64:65]
	v_pk_mul_f32 v[64:65], v[70:71], v[68:69]
	v_cvt_pk_bf16_f32 v48, v48, v49
	v_pk_mul_f32 v[50:51], v[50:51], v[64:65]
	v_lshlrev_b32_e32 v64, 16, v89
	v_cvt_pk_bf16_f32 v49, v50, v51
	v_mov_b32_e32 v236, v48
	v_mov_b32_e32 v237, v49
	v_lshlrev_b32_e32 v48, 16, v88
	v_mul_f32_e32 v49, 0xbfb8aa3b, v48
	v_exp_f32_e32 v50, v49
	v_and_b32_e32 v49, 0xffff0000, v88
	v_mul_f32_e32 v51, 0xbfb8aa3b, v49
	v_and_b32_e32 v65, 0xffff0000, v89
	v_exp_f32_e32 v51, v51
	v_mul_f32_e32 v66, 0xbfb8aa3b, v64
	v_mul_f32_e32 v67, 0xbfb8aa3b, v65
	v_exp_f32_e32 v66, v66
	v_exp_f32_e32 v67, v67
	v_add_f32_e32 v50, 1.0, v50
	v_add_f32_e32 v51, 1.0, v51
	v_rcp_f32_e32 v50, v50
	v_rcp_f32_e32 v51, v51
	v_add_f32_e32 v66, 1.0, v66
	v_add_f32_e32 v67, 1.0, v67
	v_rcp_f32_e32 v66, v66
	v_rcp_f32_e32 v67, v67
	v_pk_mul_f32 v[48:49], v[50:51], v[48:49]
	v_pk_mul_f32 v[50:51], v[54:55], v[0:1] op_sel_hi:[1,0]
	v_pk_mul_f32 v[48:49], v[52:53], v[48:49]
	v_pk_mul_f32 v[52:53], v[66:67], v[64:65]
	v_cvt_pk_bf16_f32 v48, v48, v49
	v_pk_mul_f32 v[50:51], v[50:51], v[52:53]
	v_lshlrev_b32_e32 v54, 16, v87
	v_cvt_pk_bf16_f32 v49, v50, v51
	v_mov_b32_e32 v238, v48
	v_mov_b32_e32 v239, v49
	s_nop 1
	v_permlane32_swap_b32 v236, v238
	v_permlane32_swap_b32 v237, v239
	global_store_dwordx4 v[226:227], v[236:239], off offset:64
	v_lshlrev_b32_e32 v48, 16, v86
	v_mul_f32_e32 v49, 0xbfb8aa3b, v48
	v_exp_f32_e32 v50, v49
	v_and_b32_e32 v49, 0xffff0000, v86
	v_mul_f32_e32 v51, 0xbfb8aa3b, v49
	v_and_b32_e32 v55, 0xffff0000, v87
	v_exp_f32_e32 v51, v51
	v_pk_mul_f32 v[52:53], v[56:57], v[0:1] op_sel_hi:[1,0]
	v_mul_f32_e32 v56, 0xbfb8aa3b, v54
	v_mul_f32_e32 v57, 0xbfb8aa3b, v55
	v_exp_f32_e32 v56, v56
	v_exp_f32_e32 v57, v57
	v_add_f32_e32 v50, 1.0, v50
	v_add_f32_e32 v51, 1.0, v51
	v_rcp_f32_e32 v50, v50
	v_rcp_f32_e32 v51, v51
	v_add_f32_e32 v56, 1.0, v56
	v_add_f32_e32 v57, 1.0, v57
	v_rcp_f32_e32 v56, v56
	v_rcp_f32_e32 v57, v57
	v_pk_mul_f32 v[48:49], v[50:51], v[48:49]
	v_pk_mul_f32 v[50:51], v[58:59], v[0:1] op_sel_hi:[1,0]
	v_pk_mul_f32 v[48:49], v[52:53], v[48:49]
	v_pk_mul_f32 v[52:53], v[56:57], v[54:55]
	v_cvt_pk_bf16_f32 v48, v48, v49
	v_pk_mul_f32 v[50:51], v[50:51], v[52:53]
	v_lshlrev_b32_e32 v54, 16, v85
	v_cvt_pk_bf16_f32 v49, v50, v51
	v_mov_b32_e32 v240, v48
	v_mov_b32_e32 v241, v49
	v_lshlrev_b32_e32 v48, 16, v84
	v_mul_f32_e32 v49, 0xbfb8aa3b, v48
	v_exp_f32_e32 v50, v49
	v_and_b32_e32 v49, 0xffff0000, v84
	v_mul_f32_e32 v51, 0xbfb8aa3b, v49
	v_and_b32_e32 v55, 0xffff0000, v85
	v_exp_f32_e32 v51, v51
	v_mul_f32_e32 v56, 0xbfb8aa3b, v54
	v_mul_f32_e32 v57, 0xbfb8aa3b, v55
	v_exp_f32_e32 v56, v56
	v_exp_f32_e32 v57, v57
	v_add_f32_e32 v50, 1.0, v50
	v_add_f32_e32 v51, 1.0, v51
	v_rcp_f32_e32 v50, v50
	v_rcp_f32_e32 v51, v51
	v_add_f32_e32 v56, 1.0, v56
	v_add_f32_e32 v57, 1.0, v57
	v_rcp_f32_e32 v56, v56
	v_rcp_f32_e32 v57, v57
	v_pk_mul_f32 v[52:53], v[60:61], v[0:1] op_sel_hi:[1,0]
	v_pk_mul_f32 v[48:49], v[50:51], v[48:49]
	v_pk_mul_f32 v[50:51], v[62:63], v[0:1] op_sel_hi:[1,0]
	v_pk_mul_f32 v[48:49], v[52:53], v[48:49]
	v_pk_mul_f32 v[52:53], v[56:57], v[54:55]
	v_cvt_pk_bf16_f32 v48, v48, v49
	v_pk_mul_f32 v[50:51], v[50:51], v[52:53]
	v_lshlrev_b32_e32 v52, 16, v83
	v_cvt_pk_bf16_f32 v49, v50, v51
	v_mov_b32_e32 v242, v48
	v_mov_b32_e32 v243, v49
	s_nop 1
	v_permlane32_swap_b32 v240, v242
	v_permlane32_swap_b32 v241, v243
; __device__ __forceinline__ float silu_f(float z) { return z * __builtin_amdgcn_rcpf(1.0f + __builtin_amdgcn_exp2f(-LOG2E * z)); }
; __device__ __forceinline__ float bf_lo(unsigned v) { return __uint_as_float(v << 16); }
; __device__ __forceinline__ float bf_hi(unsigned v) { return __uint_as_float(v & 0xffff0000u); }
; template <int MODE>
; __device__ __forceinline__ void attn_unit(const Params& P, LAS unsigned char* lds, const int b, const int h, const int qb) {
;     ...
;     if (FOX) {
; #pragma unroll
;         for (int d = 0; d < 4; ++d)
; #pragma unroll
;             for (int a = 0; a < 4; ++a) { const int d0 = 32 * d + 8 * a + 4 * hh; const u32x2 z2 = zv[d][a];
;                 const float o0 = O[d][4 * a] * inv1 * silu_f(bf_lo(z2.x)), o1 = O[d][4 * a + 1] * inv1 * silu_f(bf_hi(z2.x));
;                 const float o2 = O[d][4 * a + 2] * inv1 * silu_f(bf_lo(z2.y)), o3 = O[d][4 * a + 3] * inv1 * silu_f(bf_hi(z2.y));
;                 u32x2 ov; ov.x = cvt_pk_bf16(o0, o1); ov.y = cvt_pk_bf16(o2, o3); *(u32x2*)(mix + d0) = ov; }
	global_store_dwordx4 v[226:227], v[240:243], off offset:96
	v_lshlrev_b32_e32 v48, 16, v82
	v_mul_f32_e32 v49, 0xbfb8aa3b, v48
	v_exp_f32_e32 v50, v49
	v_and_b32_e32 v49, 0xffff0000, v82
	v_mul_f32_e32 v51, 0xbfb8aa3b, v49
	v_and_b32_e32 v53, 0xffff0000, v83
	v_exp_f32_e32 v51, v51
	v_mul_f32_e32 v54, 0xbfb8aa3b, v52
	v_mul_f32_e32 v55, 0xbfb8aa3b, v53
	v_exp_f32_e32 v54, v54
	v_exp_f32_e32 v55, v55
	v_add_f32_e32 v50, 1.0, v50
	v_add_f32_e32 v51, 1.0, v51
	v_rcp_f32_e32 v50, v50
	v_rcp_f32_e32 v51, v51
	v_add_f32_e32 v54, 1.0, v54
	v_add_f32_e32 v55, 1.0, v55
	v_rcp_f32_e32 v54, v54
	v_rcp_f32_e32 v55, v55
	v_pk_mul_f32 v[48:49], v[50:51], v[48:49]
	s_nop 0
	v_pk_mul_f32 v[32:33], v[32:33], v[48:49]
	v_pk_mul_f32 v[48:49], v[54:55], v[52:53]
	v_cvt_pk_bf16_f32 v32, v32, v33
	v_pk_mul_f32 v[34:35], v[34:35], v[48:49]
	v_lshlrev_b32_e32 v48, 16, v81
	v_cvt_pk_bf16_f32 v33, v34, v35
	v_mov_b32_e32 v236, v32
	v_mov_b32_e32 v237, v33
	v_lshlrev_b32_e32 v32, 16, v80
	v_mul_f32_e32 v33, 0xbfb8aa3b, v32
	v_exp_f32_e32 v34, v33
	v_and_b32_e32 v33, 0xffff0000, v80
	v_mul_f32_e32 v35, 0xbfb8aa3b, v33
	v_and_b32_e32 v49, 0xffff0000, v81
	v_exp_f32_e32 v35, v35
	v_mul_f32_e32 v50, 0xbfb8aa3b, v48
	v_mul_f32_e32 v51, 0xbfb8aa3b, v49
	v_exp_f32_e32 v50, v50
	v_exp_f32_e32 v51, v51
	v_add_f32_e32 v34, 1.0, v34
	v_add_f32_e32 v35, 1.0, v35
	v_rcp_f32_e32 v34, v34
	v_rcp_f32_e32 v35, v35
	v_add_f32_e32 v50, 1.0, v50
	v_add_f32_e32 v51, 1.0, v51
	v_rcp_f32_e32 v50, v50
	v_rcp_f32_e32 v51, v51
	v_pk_mul_f32 v[32:33], v[34:35], v[32:33]
	v_pk_mul_f32 v[34:35], v[38:39], v[0:1] op_sel_hi:[1,0]
	v_pk_mul_f32 v[32:33], v[36:37], v[32:33]
	v_pk_mul_f32 v[36:37], v[50:51], v[48:49]
	v_cvt_pk_bf16_f32 v32, v32, v33
	v_pk_mul_f32 v[34:35], v[34:35], v[36:37]
	v_and_b32_e32 v37, 0xffff0000, v15
	v_cvt_pk_bf16_f32 v33, v34, v35
	v_mov_b32_e32 v238, v32
	v_mov_b32_e32 v239, v33
	s_nop 1
	v_permlane32_swap_b32 v236, v238
	v_permlane32_swap_b32 v237, v239
	global_store_dwordx4 v[226:227], v[236:239], off offset:128
	v_lshlrev_b32_e32 v32, 16, v14
	v_mul_f32_e32 v33, 0xbfb8aa3b, v32
	v_exp_f32_e32 v34, v33
	v_and_b32_e32 v33, 0xffff0000, v14
	v_mul_f32_e32 v14, 0xbfb8aa3b, v33
	v_exp_f32_e32 v36, v14
	v_add_f32_e32 v14, 1.0, v34
	v_pk_mul_f32 v[34:35], v[40:41], v[0:1] op_sel_hi:[1,0]
	v_rcp_f32_e32 v14, v14
	v_add_f32_e32 v38, 1.0, v36
	v_lshlrev_b32_e32 v36, 16, v15
	v_mul_f32_e32 v15, 0xbfb8aa3b, v36
	v_exp_f32_e32 v39, v15
	v_mul_f32_e32 v15, 0xbfb8aa3b, v37
	v_exp_f32_e32 v40, v15
	v_rcp_f32_e32 v15, v38
	v_add_f32_e32 v38, 1.0, v39
	v_rcp_f32_e32 v38, v38
	v_add_f32_e32 v39, 1.0, v40
	v_rcp_f32_e32 v39, v39
	v_pk_mul_f32 v[14:15], v[14:15], v[32:33]
	v_pk_mul_f32 v[32:33], v[42:43], v[0:1] op_sel_hi:[1,0]
	v_pk_mul_f32 v[14:15], v[34:35], v[14:15]
	v_pk_mul_f32 v[34:35], v[38:39], v[36:37]
	v_cvt_pk_bf16_f32 v14, v14, v15
	v_pk_mul_f32 v[32:33], v[32:33], v[34:35]
	v_and_b32_e32 v35, 0xffff0000, v13
	v_cvt_pk_bf16_f32 v15, v32, v33
	v_mov_b32_e32 v240, v14
	v_mov_b32_e32 v241, v15
	v_lshlrev_b32_e32 v14, 16, v12
	v_mul_f32_e32 v15, 0xbfb8aa3b, v14
	v_exp_f32_e32 v32, v15
	v_and_b32_e32 v15, 0xffff0000, v12
	v_mul_f32_e32 v12, 0xbfb8aa3b, v15
	v_exp_f32_e32 v34, v12
	v_add_f32_e32 v12, 1.0, v32
	v_rcp_f32_e32 v12, v12
	v_pk_mul_f32 v[32:33], v[44:45], v[0:1] op_sel_hi:[1,0]
	v_add_f32_e32 v36, 1.0, v34
	v_lshlrev_b32_e32 v34, 16, v13
	v_mul_f32_e32 v13, 0xbfb8aa3b, v34
	v_exp_f32_e32 v37, v13
	v_mul_f32_e32 v13, 0xbfb8aa3b, v35
	v_exp_f32_e32 v38, v13
	v_rcp_f32_e32 v13, v36
	v_add_f32_e32 v36, 1.0, v37
	v_rcp_f32_e32 v36, v36
	v_add_f32_e32 v37, 1.0, v38
	v_rcp_f32_e32 v37, v37
	v_pk_mul_f32 v[12:13], v[12:13], v[14:15]
	v_pk_mul_f32 v[14:15], v[46:47], v[0:1] op_sel_hi:[1,0]
	v_pk_mul_f32 v[12:13], v[32:33], v[12:13]
	v_pk_mul_f32 v[32:33], v[36:37], v[34:35]
	v_cvt_pk_bf16_f32 v12, v12, v13
	v_pk_mul_f32 v[14:15], v[14:15], v[32:33]
	s_nop 0
	v_cvt_pk_bf16_f32 v13, v14, v15
	v_mov_b32_e32 v242, v12
	v_mov_b32_e32 v243, v13
	s_nop 1
	v_permlane32_swap_b32 v240, v242
	v_permlane32_swap_b32 v241, v243
	global_store_dwordx4 v[226:227], v[240:243], off offset:160
; __device__ __forceinline__ float silu_f(float z) { return z * __builtin_amdgcn_rcpf(1.0f + __builtin_amdgcn_exp2f(-LOG2E * z)); }
; __device__ __forceinline__ float bf_lo(unsigned v) { return __uint_as_float(v << 16); }
; __device__ __forceinline__ float bf_hi(unsigned v) { return __uint_as_float(v & 0xffff0000u); }
; template <int MODE>
; __device__ __forceinline__ void attn_unit(const Params& P, LAS unsigned char* lds, const int b, const int h, const int qb) {
;     ...
;     if (FOX) {
; #pragma unroll
;         for (int d = 0; d < 4; ++d)
; #pragma unroll
;             for (int a = 0; a < 4; ++a) { const int d0 = 32 * d + 8 * a + 4 * hh; const u32x2 z2 = zv[d][a];
;                 const float o0 = O[d][4 * a] * inv1 * silu_f(bf_lo(z2.x)), o1 = O[d][4 * a + 1] * inv1 * silu_f(bf_hi(z2.x));
;                 const float o2 = O[d][4 * a + 2] * inv1 * silu_f(bf_lo(z2.y)), o3 = O[d][4 * a + 3] * inv1 * silu_f(bf_hi(z2.y));
;                 u32x2 ov; ov.x = cvt_pk_bf16(o0, o1); ov.y = cvt_pk_bf16(o2, o3); *(u32x2*)(mix + d0) = ov; }
;         __syncthreads();
	v_lshlrev_b32_e32 v12, 16, v10
	v_mul_f32_e32 v13, 0xbfb8aa3b, v12
	v_exp_f32_e32 v14, v13
	v_and_b32_e32 v13, 0xffff0000, v10
	v_mul_f32_e32 v10, 0xbfb8aa3b, v13
	v_exp_f32_e32 v32, v10
	v_add_f32_e32 v10, 1.0, v14
	v_pk_mul_f32 v[14:15], v[16:17], v[0:1] op_sel_hi:[1,0]
	v_lshlrev_b32_e32 v16, 16, v11
	v_and_b32_e32 v17, 0xffff0000, v11
	v_mul_f32_e32 v11, 0xbfb8aa3b, v16
	v_exp_f32_e32 v33, v11
	v_mul_f32_e32 v11, 0xbfb8aa3b, v17
	v_exp_f32_e32 v34, v11
	v_add_f32_e32 v32, 1.0, v32
	v_rcp_f32_e32 v10, v10
	v_rcp_f32_e32 v11, v32
	v_add_f32_e32 v32, 1.0, v33
	v_add_f32_e32 v33, 1.0, v34
	v_rcp_f32_e32 v32, v32
	v_rcp_f32_e32 v33, v33
	v_pk_mul_f32 v[10:11], v[10:11], v[12:13]
	v_pk_mul_f32 v[12:13], v[18:19], v[0:1] op_sel_hi:[1,0]
	v_pk_mul_f32 v[10:11], v[14:15], v[10:11]
	v_pk_mul_f32 v[14:15], v[32:33], v[16:17]
	v_cvt_pk_bf16_f32 v10, v10, v11
	v_pk_mul_f32 v[12:13], v[12:13], v[14:15]
	v_and_b32_e32 v15, 0xffff0000, v9
	v_cvt_pk_bf16_f32 v11, v12, v13
	v_mov_b32_e32 v236, v10
	v_mov_b32_e32 v237, v11
	v_lshlrev_b32_e32 v10, 16, v8
	v_mul_f32_e32 v11, 0xbfb8aa3b, v10
	v_exp_f32_e32 v12, v11
	v_and_b32_e32 v11, 0xffff0000, v8
	v_mul_f32_e32 v8, 0xbfb8aa3b, v11
	v_exp_f32_e32 v14, v8
	v_add_f32_e32 v8, 1.0, v12
	v_rcp_f32_e32 v8, v8
	v_pk_mul_f32 v[12:13], v[20:21], v[0:1] op_sel_hi:[1,0]
	v_add_f32_e32 v16, 1.0, v14
	v_lshlrev_b32_e32 v14, 16, v9
	v_mul_f32_e32 v9, 0xbfb8aa3b, v14
	v_exp_f32_e32 v17, v9
	v_mul_f32_e32 v9, 0xbfb8aa3b, v15
	v_exp_f32_e32 v18, v9
	v_rcp_f32_e32 v9, v16
	v_add_f32_e32 v16, 1.0, v17
	v_rcp_f32_e32 v16, v16
	v_add_f32_e32 v17, 1.0, v18
	v_rcp_f32_e32 v17, v17
	v_pk_mul_f32 v[8:9], v[8:9], v[10:11]
	v_pk_mul_f32 v[10:11], v[22:23], v[0:1] op_sel_hi:[1,0]
	v_pk_mul_f32 v[8:9], v[12:13], v[8:9]
	v_pk_mul_f32 v[12:13], v[16:17], v[14:15]
	v_cvt_pk_bf16_f32 v8, v8, v9
	v_pk_mul_f32 v[10:11], v[10:11], v[12:13]
	v_and_b32_e32 v13, 0xffff0000, v7
	v_cvt_pk_bf16_f32 v9, v10, v11
	v_mov_b32_e32 v238, v8
	v_mov_b32_e32 v239, v9
	s_nop 1
	v_permlane32_swap_b32 v236, v238
	v_permlane32_swap_b32 v237, v239
	global_store_dwordx4 v[226:227], v[236:239], off offset:192
	v_lshlrev_b32_e32 v8, 16, v6
	v_mul_f32_e32 v9, 0xbfb8aa3b, v8
	v_exp_f32_e32 v10, v9
	v_and_b32_e32 v9, 0xffff0000, v6
	v_mul_f32_e32 v6, 0xbfb8aa3b, v9
	v_exp_f32_e32 v12, v6
	v_add_f32_e32 v6, 1.0, v10
	v_rcp_f32_e32 v6, v6
	v_pk_mul_f32 v[10:11], v[24:25], v[0:1] op_sel_hi:[1,0]
	v_add_f32_e32 v14, 1.0, v12
	v_lshlrev_b32_e32 v12, 16, v7
	v_mul_f32_e32 v7, 0xbfb8aa3b, v12
	v_exp_f32_e32 v15, v7
	v_mul_f32_e32 v7, 0xbfb8aa3b, v13
	v_exp_f32_e32 v16, v7
	v_rcp_f32_e32 v7, v14
	v_add_f32_e32 v14, 1.0, v15
	v_rcp_f32_e32 v14, v14
	v_add_f32_e32 v15, 1.0, v16
	v_rcp_f32_e32 v15, v15
	v_pk_mul_f32 v[6:7], v[6:7], v[8:9]
	v_pk_mul_f32 v[8:9], v[26:27], v[0:1] op_sel_hi:[1,0]
	v_pk_mul_f32 v[6:7], v[10:11], v[6:7]
	v_pk_mul_f32 v[10:11], v[14:15], v[12:13]
	v_cvt_pk_bf16_f32 v6, v6, v7
	v_pk_mul_f32 v[8:9], v[8:9], v[10:11]
	v_and_b32_e32 v11, 0xffff0000, v3
	v_cvt_pk_bf16_f32 v7, v8, v9
	v_mov_b32_e32 v240, v6
	v_mov_b32_e32 v241, v7
	v_lshlrev_b32_e32 v6, 16, v2
	v_mul_f32_e32 v7, 0xbfb8aa3b, v6
	v_exp_f32_e32 v8, v7
	v_and_b32_e32 v7, 0xffff0000, v2
	v_mul_f32_e32 v2, 0xbfb8aa3b, v7
	v_exp_f32_e32 v10, v2
	v_add_f32_e32 v2, 1.0, v8
	v_rcp_f32_e32 v2, v2
	v_pk_mul_f32 v[8:9], v[28:29], v[0:1] op_sel_hi:[1,0]
	v_add_f32_e32 v12, 1.0, v10
	v_lshlrev_b32_e32 v10, 16, v3
	v_mul_f32_e32 v3, 0xbfb8aa3b, v10
	v_exp_f32_e32 v13, v3
	v_mul_f32_e32 v3, 0xbfb8aa3b, v11
	v_exp_f32_e32 v14, v3
	v_rcp_f32_e32 v3, v12
	v_add_f32_e32 v12, 1.0, v13
	v_rcp_f32_e32 v12, v12
	v_add_f32_e32 v13, 1.0, v14
	v_rcp_f32_e32 v13, v13
	v_pk_mul_f32 v[2:3], v[2:3], v[6:7]
	v_pk_mul_f32 v[6:7], v[30:31], v[0:1] op_sel_hi:[1,0]
	v_pk_mul_f32 v[2:3], v[8:9], v[2:3]
	v_pk_mul_f32 v[8:9], v[12:13], v[10:11]
	v_cvt_pk_bf16_f32 v2, v2, v3
	v_pk_mul_f32 v[6:7], v[6:7], v[8:9]
	s_nop 0
	v_cvt_pk_bf16_f32 v3, v6, v7
	v_mov_b32_e32 v242, v2
	v_mov_b32_e32 v243, v3
	s_nop 1
	v_permlane32_swap_b32 v240, v242
	v_permlane32_swap_b32 v241, v243
	global_store_dwordx4 v[226:227], v[240:243], off offset:224
	s_barrier
